# attention loop DMA via scalar base + 32-bit lane offset (saddr form), scalar base advance instead of 64-bit VALU address adds
# speedup vs baseline: 1.0079x; 1.0040x over previous
.LBB0_841:
	s_ashr_i32 s4, s74, 9
	s_lshl_b32 s1, s74, 8
	s_lshl_b32 s0, s4, 13
	s_and_b32 s1, s1, 0x1f00
	s_or_b32 s0, s0, s1
	s_ashr_i32 s1, s0, 31
	s_lshl_b32 s5, s74, 1
	s_lshl_b64 s[8:9], s[0:1], 10
	s_and_b32 s80, s5, 0x380
	s_lshl_b64 s[0:1], s[0:1], 11
	s_add_u32 s0, s30, s0
	s_addc_u32 s1, s31, s1
	s_lshl_b32 s5, s74, 2
	s_and_b32 s5, s5, 0x780
	s_add_u32 s12, s0, s5
	s_addc_u32 s13, s1, 0
	s_mul_i32 s1, s4, 0x1080000
	s_mul_hi_i32 s0, s4, 0x1080000
	s_add_u32 s6, s35, s1
	s_addc_u32 s7, s54, s0
	s_add_u32 s6, s6, s5
	s_addc_u32 s7, s7, 0
	s_add_u32 s1, s55, s1
	s_addc_u32 s0, s60, s0
	s_lshl_b32 s5, s80, 1
	v_mov_b32_e32 v12, v223
	s_add_u32 s14, s1, s5
	s_addc_u32 s15, s0, 0
	v_readfirstlane_b32 s5, v12
	s_ashr_i32 s75, s5, 6
	s_lshl_b32 s0, s75, 5
	s_ashr_i32 s1, s0, 31
	s_lshl_b64 s[10:11], s[0:1], 10
	s_lshl_b64 s[0:1], s[0:1], 11
	v_and_b32_e32 v213, 63, v12
	s_add_u32 s22, s12, s0
	s_addc_u32 s23, s13, s1
	v_lshlrev_b32_e32 v208, 11, v213
	s_lshl_b32 s12, s75, 3
	v_lshl_add_u64 v[0:1], s[6:7], 0, v[208:209]
	s_ashr_i32 s13, s12, 31
	v_lshl_add_u64 v[204:205], s[12:13], 1, v[0:1]
	s_lshl_b32 s1, s75, 4
	v_bfe_u32 v0, v12, 2, 4
	v_and_or_b32 v0, s1, 48, v0
	s_ashr_i32 s1, s5, 3
	s_and_b32 s6, s1, 0xffffffe0
	s_and_b32 s0, s5, 0x3fffffc0
	s_ashr_i32 s7, s6, 31
	s_lshl_b32 s1, s75, 10
	v_lshlrev_b32_e32 v0, 11, v0
	v_mov_b32_e32 v1, v209
	v_lshlrev_b32_e32 v218, 3, v12
	s_cmp_lg_u32 0, -1
	v_lshl_add_u64 v[0:1], s[14:15], 0, v[0:1]
	v_and_b32_e32 v219, 24, v218
	s_cselect_b32 s5, 0, 0
	v_lshl_add_u64 v[0:1], s[6:7], 1, v[0:1]
	v_lshlrev_b32_e32 v2, 1, v219
	v_mov_b32_e32 v3, v209
	s_add_i32 s26, s1, s5
	s_mov_b32 s1, m0
	s_mov_b32 m0, s26
	s_nop 0
	global_load_lds_dwordx4 v[204:205], off
	s_mov_b32 m0, s1
	v_bfe_u32 v217, v12, 5, 1
	v_lshl_add_u64 v[224:225], v[0:1], 0, v[2:3]
	s_add_i32 s27, s26, 0x6000
	s_mov_b32 s1, m0
	s_mov_b32 m0, s27
	s_nop 0
	global_load_lds_dwordx4 v[224:225], off
	s_mov_b32 m0, s1
	v_and_b32_e32 v216, 31, v12
	v_lshl_add_u64 v[226:227], v[224:225], 0, s[92:93]
	s_add_i32 s1, s26, 0x8000
	s_mov_b32 s5, m0
	s_mov_b32 m0, s1
	s_nop 0
	global_load_lds_dwordx4 v[226:227], off
	s_mov_b32 m0, s5
	v_lshl_add_u64 v[0:1], v[204:205], 0, s[58:59]
	v_lshlrev_b32_e32 v221, 4, v217
	s_add_i32 s1, s26, 0x2000
	s_mov_b32 s5, m0
	s_mov_b32 m0, s1
	s_nop 0
	global_load_lds_dwordx4 v[0:1], off
	s_mov_b32 m0, s5
	v_lshl_or_b32 v0, v216, 11, v221
	global_load_dwordx4 v[156:159], v0, s[22:23]
	global_load_dwordx4 v[152:155], v0, s[22:23] offset:32
	global_load_dwordx4 v[148:151], v0, s[22:23] offset:64
	global_load_dwordx4 v[144:147], v0, s[22:23] offset:96
	v_lshlrev_b32_e32 v0, 10, v217
	v_lshlrev_b32_e32 v1, 4, v216
	v_add3_u32 v214, 0, v0, v1
	v_lshl_add_u64 v[0:1], v[204:205], 0, s[90:91]
	s_add_i32 s1, s26, 0x4000
	s_mov_b32 s5, m0
	s_mov_b32 m0, s1
	s_nop 0
	global_load_lds_dwordx4 v[0:1], off
	s_mov_b32 m0, s5
	s_waitcnt vmcnt(4) lgkmcnt(0)
	s_barrier
	ds_read_b128 v[0:3], v214
	ds_read_b128 v[4:7], v214 offset:512
	s_mov_b32 s36, 0
	s_mov_b32 s37, s36
	s_mov_b32 s38, s36
	s_mov_b32 s39, s36
	s_mov_b32 s40, s36
	s_mov_b32 s41, s36
	s_mov_b32 s42, s36
	s_mov_b32 s43, s36
	s_mov_b32 s44, s36
	s_mov_b32 s45, s36
	s_mov_b32 s46, s36
	s_mov_b32 s47, s36
	s_mov_b32 s48, s36
	s_mov_b32 s49, s36
	s_mov_b32 s50, s36
	s_mov_b32 s51, s36
	v_lshlrev_b32_e32 v52, 1, v12
	v_lshlrev_b32_e32 v53, 4, v12
	s_lshl_b32 s0, s0, 2
	v_and_b32_e32 v210, 32, v52
	v_and_b32_e32 v52, 0xc0, v53
	v_lshl_or_b32 v220, v217, 8, v52
	v_add_u32_e32 v52, 0, v210
	v_add3_u32 v211, v52, v219, v220
	s_mov_b32 s5, -1
	s_movk_i32 s23, 0x2000
	s_waitcnt vmcnt(0) lgkmcnt(0)
	v_mfma_f32_32x32x16_bf16 v[32:47], v[0:3], v[156:159], 0
	s_movk_i32 s22, 0x4000
	v_cmp_gt_u32_e64 s[6:7], 32, v213
	v_lshl_add_u64 v[228:229], v[224:225], 0, s[18:19]
	v_mov_b32_e32 v215, 0
	v_mfma_f32_32x32x16_bf16 v[16:31], v[4:7], v[156:159], 0
	ds_read_b128 v[0:3], v214 offset:2048
	ds_read_b128 v[4:7], v214 offset:2560
	s_waitcnt lgkmcnt(1)
	v_mfma_f32_32x32x16_bf16 v[32:47], v[0:3], v[152:155], v[32:47]
	ds_read_b128 v[0:3], v214 offset:4608
	ds_read_b128 v[8:11], v214 offset:4096
	s_waitcnt lgkmcnt(2)
	v_mfma_f32_32x32x16_bf16 v[16:31], v[4:7], v[152:155], v[16:31]
	ds_read_b128 v[48:51], v214 offset:6656
	ds_read_b128 v[4:7], v214 offset:6144
	s_waitcnt lgkmcnt(2)
	v_mfma_f32_32x32x16_bf16 v[32:47], v[8:11], v[148:151], v[32:47]
	v_mfma_f32_32x32x16_bf16 v[16:31], v[0:3], v[148:151], v[16:31]
	s_waitcnt lgkmcnt(0)
	v_mfma_f32_32x32x16_bf16 v[32:47], v[4:7], v[144:147], v[32:47]
	v_mov_b64_e32 v[0:1], s[36:37]
	v_mov_b64_e32 v[2:3], s[38:39]
	v_mov_b64_e32 v[4:5], s[40:41]
	v_mov_b64_e32 v[6:7], s[42:43]
	v_mov_b64_e32 v[8:9], s[44:45]
	v_mov_b64_e32 v[10:11], s[46:47]
	v_mov_b64_e32 v[12:13], s[48:49]
	v_mfma_f32_32x32x16_bf16 v[16:31], v[48:51], v[144:147], v[16:31]
	s_nop 15
	s_nop 7
	s_waitcnt vmcnt(0) lgkmcnt(0)
	s_barrier
	v_mov_b64_e32 v[14:15], s[50:51]
	v_max3_f32 v48, v32, v33, v16
	v_max3_f32 v49, v34, v35, v17
	s_add_i32 s37, s0, 0
	v_max3_f32 v48, v48, v18, v19
	v_max3_f32 v49, v49, v38, v39
	s_add_i32 s37, s37, 0x12000
	v_max3_f32 v48, v48, v36, v37
	v_max3_f32 v49, v49, v22, v23
	v_lshl_add_u32 v212, v216, 2, s37
	v_max3_f32 v48, v48, v20, v21
	v_max3_f32 v49, v49, v42, v43
	s_nop 0
	v_max3_f32 v48, v48, v40, v41
	v_max3_f32 v49, v49, v26, v27
	s_nop 0
	v_max3_f32 v48, v48, v24, v25
	v_max3_f32 v49, v49, v46, v47
	s_nop 0
	v_max3_f32 v48, v48, v44, v45
	v_max3_f32 v49, v49, v30, v31
	s_nop 0
	v_max3_f32 v48, v48, v28, v29
	s_nop 0
	v_max_f32_e32 v48, v48, v49
	s_nop 0
	v_mov_b32_e32 v49, v48
	s_nop 1
	v_permlane32_swap_b32_e32 v48, v49
	v_max_f32_e32 v48, v48, v49
	s_nop 0
	v_sub_f32_e32 v16, v16, v48
	v_sub_f32_e32 v17, v17, v48
	v_sub_f32_e32 v32, v32, v48
	v_sub_f32_e32 v33, v33, v48
	v_sub_f32_e32 v34, v34, v48
	v_sub_f32_e32 v18, v18, v48
	s_nop 0
	v_exp_f32_e32 v64, v16
	v_exp_f32_e32 v65, v17
	v_lshl_add_u64 v[16:17], v[204:205], 0, s[18:19]
	s_mov_b32 s0, m0
	s_mov_b32 m0, s26
	s_nop 0
	global_load_lds_dwordx4 v[16:17], off
	s_mov_b32 m0, s0
	v_lshl_add_u64 v[16:17], v[224:225], 0, s[58:59]
	s_add_i32 s0, s26, 0xa000
	s_mov_b32 s1, m0
	s_mov_b32 m0, s0
	s_nop 0
	global_load_lds_dwordx4 v[16:17], off
	s_mov_b32 m0, s1
	s_mov_b64 s[0:1], 0x20080
	v_lshl_add_u64 v[16:17], v[224:225], 0, s[0:1]
	s_add_i32 s0, s26, 0xc000
	s_mov_b32 s1, m0
	s_mov_b32 m0, s0
	s_nop 0
	global_load_lds_dwordx4 v[16:17], off
	s_mov_b32 m0, s1
	ds_read_b128 v[96:99], v214 offset:8192
	ds_read_b128 v[112:115], v214 offset:8704
	ds_read_b128 v[180:183], v214 offset:10240
	ds_read_b128 v[176:179], v214 offset:10752
	ds_read_b128 v[172:175], v214 offset:12288
	ds_read_b128 v[168:171], v214 offset:12800
	ds_read_b128 v[164:167], v214 offset:14336
	ds_read_b128 v[160:163], v214 offset:14848
	v_sub_f32_e32 v35, v35, v48
	v_sub_f32_e32 v19, v19, v48
	v_sub_f32_e32 v36, v36, v48
	v_sub_f32_e32 v20, v20, v48
	v_sub_f32_e32 v37, v37, v48
	v_sub_f32_e32 v21, v21, v48
	v_sub_f32_e32 v38, v38, v48
	v_sub_f32_e32 v22, v22, v48
	v_sub_f32_e32 v39, v39, v48
	v_sub_f32_e32 v23, v23, v48
	v_sub_f32_e32 v40, v40, v48
	v_sub_f32_e32 v24, v24, v48
	v_sub_f32_e32 v41, v41, v48
	v_sub_f32_e32 v25, v25, v48
	v_sub_f32_e32 v42, v42, v48
	v_sub_f32_e32 v26, v26, v48
	v_sub_f32_e32 v43, v43, v48
	v_sub_f32_e32 v27, v27, v48
	v_sub_f32_e32 v44, v44, v48
	v_sub_f32_e32 v28, v28, v48
	v_sub_f32_e32 v45, v45, v48
	v_sub_f32_e32 v29, v29, v48
	v_sub_f32_e32 v46, v46, v48
	v_sub_f32_e32 v30, v30, v48
	v_sub_f32_e32 v47, v47, v48
	v_sub_f32_e32 v31, v31, v48
	v_exp_f32_e32 v80, v32
	v_exp_f32_e32 v81, v33
	v_exp_f32_e32 v82, v34
	v_exp_f32_e32 v83, v35
	v_exp_f32_e32 v84, v36
	v_exp_f32_e32 v85, v37
	v_exp_f32_e32 v86, v38
	v_exp_f32_e32 v87, v39
	v_exp_f32_e32 v88, v40
	v_exp_f32_e32 v89, v41
	v_exp_f32_e32 v90, v42
	v_exp_f32_e32 v91, v43
	v_exp_f32_e32 v92, v44
	v_exp_f32_e32 v93, v45
	v_exp_f32_e32 v94, v46
	v_exp_f32_e32 v95, v47
	v_exp_f32_e32 v66, v18
	v_exp_f32_e32 v67, v19
	v_exp_f32_e32 v68, v20
	v_exp_f32_e32 v69, v21
	v_exp_f32_e32 v70, v22
	v_exp_f32_e32 v71, v23
	v_exp_f32_e32 v72, v24
	v_exp_f32_e32 v73, v25
	v_exp_f32_e32 v74, v26
	v_exp_f32_e32 v75, v27
	v_exp_f32_e32 v76, v28
	v_exp_f32_e32 v77, v29
	v_exp_f32_e32 v78, v30
	v_exp_f32_e32 v79, v31
	s_waitcnt vmcnt(3) lgkmcnt(0)
	s_barrier
	s_mov_b64 s[0:1], 0x60080
	v_add_f32_e32 v222, v209, v48
	v_lshl_add_u64 v[206:207], v[224:225], 0, s[0:1]
	s_mov_b64 s[0:1], 0xa0000
	v_mov_b64_e32 v[62:63], v[14:15]
	v_mov_b64_e32 v[46:47], v[14:15]
	v_mov_b64_e32 v[30:31], v[14:15]
	v_lshl_add_u64 v[230:231], v[204:205], 0, s[0:1]
	v_mov_b64_e32 v[60:61], v[12:13]
	v_mov_b64_e32 v[58:59], v[10:11]
	v_mov_b64_e32 v[56:57], v[8:9]
	v_mov_b64_e32 v[54:55], v[6:7]
	v_mov_b64_e32 v[52:53], v[4:5]
	v_mov_b64_e32 v[50:51], v[2:3]
	v_mov_b64_e32 v[48:49], v[0:1]
	v_mov_b64_e32 v[44:45], v[12:13]
	v_mov_b64_e32 v[42:43], v[10:11]
	v_mov_b64_e32 v[40:41], v[8:9]
	v_mov_b64_e32 v[38:39], v[6:7]
	v_mov_b64_e32 v[36:37], v[4:5]
	v_mov_b64_e32 v[34:35], v[2:3]
	v_mov_b64_e32 v[32:33], v[0:1]
	v_mov_b64_e32 v[28:29], v[12:13]
	v_mov_b64_e32 v[26:27], v[10:11]
	v_mov_b64_e32 v[24:25], v[8:9]
	v_mov_b64_e32 v[22:23], v[6:7]
	v_mov_b64_e32 v[20:21], v[4:5]
	v_mov_b64_e32 v[18:19], v[2:3]
	v_mov_b64_e32 v[16:17], v[0:1]
	v_sub_f32_e32 v236, 0, v222
	v_sub_f32_e32 v237, 0, v222
	v_sub_f32_e32 v238, 0, v222
	v_sub_f32_e32 v239, 0, v222
	v_sub_f32_e32 v240, 0, v222
	v_sub_f32_e32 v241, 0, v222
	v_sub_f32_e32 v242, 0, v222
	v_sub_f32_e32 v243, 0, v222
	v_sub_f32_e32 v244, 0, v222
	v_sub_f32_e32 v245, 0, v222
	v_sub_f32_e32 v246, 0, v222
	v_sub_f32_e32 v247, 0, v222
	v_sub_f32_e32 v248, 0, v222
	v_sub_f32_e32 v249, 0, v222
	v_sub_f32_e32 v250, 0, v222
	v_sub_f32_e32 v251, 0, v222
	v_readfirstlane_b32 s98, v230
	v_readfirstlane_b32 s99, v231
	v_readfirstlane_b32 s86, v228
	v_readfirstlane_b32 s87, v229
	v_readfirstlane_b32 s90, v206
	v_readfirstlane_b32 s91, v207
	s_nop 1
	v_subrev_u32_e32 v230, s98, v230
	v_subrev_u32_e32 v228, s86, v228
	v_subrev_u32_e32 v206, s90, v206
	v_mov_b32_e32 v207, 0
	s_add_u32 s98, s98, 0xfffe0000
	s_addc_u32 s99, s99, -1
	s_add_u32 s86, s86, 0xfffe0000
	s_addc_u32 s87, s87, -1
	s_add_u32 s90, s90, 0xfffe0000
	s_addc_u32 s91, s91, -1
.LBB0_842:
	s_lshl_b32 s0, s36, 1
	v_add_u32_e32 v200, s0, v211
	s_setprio 1
	ds_read_b64_tr_b16 v[196:197], v200 offset:24576
	ds_read_b64_tr_b16 v[198:199], v200 offset:25088
	v_add_f32_e32 v100, v80, v81
	v_add_f32_e32 v100, v82, v100
	v_add_f32_e32 v100, v83, v100
	v_add_f32_e32 v100, v84, v100
	v_add_f32_e32 v116, v85, v100
	s_waitcnt lgkmcnt(9)
	v_mfma_f32_32x32x16_bf16 v[96:111], v[96:99], v[156:159], v[236:251]
	v_cvt_pk_bf16_f32 v140, v80, v81
	v_cvt_pk_bf16_f32 v141, v82, v83
	ds_read_b64_tr_b16 v[188:189], v200 offset:28672
	ds_read_b64_tr_b16 v[190:191], v200 offset:29184
	v_add_f32_e32 v80, v86, v116
	v_add_f32_e32 v80, v87, v80
	v_add_f32_e32 v80, v88, v80
	v_add_f32_e32 v80, v89, v80
	v_cvt_pk_bf16_f32 v142, v84, v85
	v_cvt_pk_bf16_f32 v143, v86, v87
	s_waitcnt lgkmcnt(10)
	v_mfma_f32_32x32x16_bf16 v[112:127], v[112:115], v[156:159], v[236:251]
	ds_read_b64_tr_b16 v[184:185], v200 offset:25600
	ds_read_b64_tr_b16 v[186:187], v200 offset:26112
	s_waitcnt lgkmcnt(11)
	v_mfma_f32_32x32x16_bf16 v[96:111], v[180:183], v[152:155], v[96:111]
	v_add_f32_e32 v80, v90, v80
	v_add_f32_e32 v80, v91, v80
	v_add_f32_e32 v80, v92, v80
	v_add_f32_e32 v80, v93, v80
	v_cvt_pk_bf16_f32 v136, v88, v89
	v_cvt_pk_bf16_f32 v137, v90, v91
	ds_read_b64_tr_b16 v[180:181], v200 offset:29696
	ds_read_b64_tr_b16 v[182:183], v200 offset:30208
	v_add_f32_e32 v80, v94, v80
	v_add_f32_e32 v80, v95, v80
	v_add_f32_e32 v80, v64, v80
	v_add_f32_e32 v80, v65, v80
	v_cvt_pk_bf16_f32 v138, v92, v93
	v_cvt_pk_bf16_f32 v139, v94, v95
	s_waitcnt lgkmcnt(12)
	v_mfma_f32_32x32x16_bf16 v[112:127], v[176:179], v[152:155], v[112:127]
	ds_read_b64_tr_b16 v[192:193], v200 offset:26624
	ds_read_b64_tr_b16 v[194:195], v200 offset:27136
	s_waitcnt lgkmcnt(13)
	v_mfma_f32_32x32x16_bf16 v[96:111], v[172:175], v[148:151], v[96:111]
	v_add_f32_e32 v80, v66, v80
	v_add_f32_e32 v80, v67, v80
	v_add_f32_e32 v80, v68, v80
	v_add_f32_e32 v80, v69, v80
	v_cvt_pk_bf16_f32 v132, v64, v65
	v_cvt_pk_bf16_f32 v133, v66, v67
	ds_read_b64_tr_b16 v[172:173], v200 offset:30720
	ds_read_b64_tr_b16 v[174:175], v200 offset:31232
	v_add_f32_e32 v64, v70, v80
	v_add_f32_e32 v64, v71, v64
	v_add_f32_e32 v64, v72, v64
	v_add_f32_e32 v64, v73, v64
	v_cvt_pk_bf16_f32 v134, v68, v69
	v_cvt_pk_bf16_f32 v135, v70, v71
	s_waitcnt lgkmcnt(14)
	v_mfma_f32_32x32x16_bf16 v[112:127], v[168:171], v[148:151], v[112:127]
	ds_read_b64_tr_b16 v[168:169], v200 offset:27648
	ds_read_b64_tr_b16 v[170:171], v200 offset:28160
	s_waitcnt lgkmcnt(14)
	v_mfma_f32_32x32x16_bf16 v[96:111], v[164:167], v[144:147], v[96:111]
	v_add_f32_e32 v64, v74, v64
	v_add_f32_e32 v64, v75, v64
	v_add_f32_e32 v64, v76, v64
	v_add_f32_e32 v64, v77, v64
	v_cvt_pk_bf16_f32 v128, v72, v73
	v_cvt_pk_bf16_f32 v129, v74, v75
	ds_read_b64_tr_b16 v[176:177], v200 offset:31744
	ds_read_b64_tr_b16 v[178:179], v200 offset:32256
	v_add_f32_e32 v64, v78, v64
	v_mfma_f32_32x32x16_bf16 v[112:127], v[160:163], v[144:147], v[112:127]
	v_add_f32_e32 v160, v79, v64
	v_cvt_pk_bf16_f32 v130, v76, v77
	v_cvt_pk_bf16_f32 v131, v78, v79
	s_setprio 0
	s_add_i32 s0, s23, s26
	s_mov_b32 s1, m0
	s_mov_b32 m0, s0
	s_nop 0
	global_load_lds_dwordx4 v230, s[98:99]
	s_add_u32 s98, s98, 0x20000
	s_addc_u32 s99, s99, 0
	s_mov_b32 m0, s1
	s_lshl_b32 s0, s22, 1
	s_add_i32 s0, s0, s27
	s_mov_b32 s1, m0
	s_mov_b32 m0, s0
	s_nop 0
	global_load_lds_dwordx4 v228, s[86:87]
	s_add_u32 s86, s86, 0x20000
	s_addc_u32 s87, s87, 0
	s_mov_b32 m0, s1
	s_addk_i32 s0, 0x2000
	s_mov_b32 s1, m0
	s_mov_b32 m0, s0
	s_nop 0
	global_load_lds_dwordx4 v206, s[90:91]
	s_add_u32 s90, s90, 0x20000
	s_addc_u32 s91, s91, 0
	s_mov_b32 m0, s1
	v_max_f32_e32 v80, v96, v97
	v_max3_f32 v81, v98, v99, v113
	v_max3_f32 v80, v80, v112, v114
	v_max3_f32 v80, v80, v115, v100
	v_max3_f32 v81, v81, v102, v103
	v_max3_f32 v80, v80, v101, v116
	v_max3_f32 v81, v81, v118, v119
	v_max3_f32 v80, v80, v117, v104
	v_max3_f32 v81, v81, v106, v107
	v_max3_f32 v80, v80, v105, v120
	v_max3_f32 v81, v81, v122, v123
	v_max3_f32 v80, v80, v121, v108
	v_max3_f32 v81, v81, v110, v111
	v_max3_f32 v80, v80, v109, v124
	v_max3_f32 v81, v81, v126, v127
	v_max3_f32 v80, v80, v125, v81
	v_mov_b32_e32 v81, v80
	s_nop 1
	v_permlane32_swap_b32_e32 v80, v81
	v_max_f32_e32 v80, v80, v81
	v_cmp_lt_f32_e32 vcc, s56, v80
	s_cmp_lg_u64 vcc, 0
	v_add_f32_e32 v215, v215, v160
	s_cselect_b64 s[0:1], -1, 0
	s_cbranch_vccnz .LBB0_850

.LBB0_845:
	s_add_i32 s0, s22, 0x2000
	s_cmpk_lg_i32 s22, 0x4000
	s_cselect_b32 s24, s0, 0
	s_lshl_b32 s0, s23, 1
	v_add_u32_e32 v255, s0, v211
	s_setprio 1
	ds_read_b64_tr_b16 v[200:201], v255 offset:24576
	ds_read_b64_tr_b16 v[202:203], v255 offset:25088
	v_add_f32_e32 v100, v80, v81
	v_add_f32_e32 v100, v82, v100
	v_add_f32_e32 v100, v83, v100
	v_add_f32_e32 v100, v84, v100
	v_add_f32_e32 v116, v85, v100
	v_mfma_f32_32x32x16_bf16 v[96:111], v[96:99], v[156:159], v[236:251]
	v_cvt_pk_bf16_f32 v140, v80, v81
	v_cvt_pk_bf16_f32 v141, v82, v83
	ds_read_b64_tr_b16 v[176:177], v255 offset:28672
	ds_read_b64_tr_b16 v[178:179], v255 offset:29184
	v_add_f32_e32 v80, v86, v116
	v_add_f32_e32 v80, v87, v80
	v_add_f32_e32 v80, v88, v80
	v_add_f32_e32 v80, v89, v80
	v_cvt_pk_bf16_f32 v142, v84, v85
	v_cvt_pk_bf16_f32 v143, v86, v87
	v_mfma_f32_32x32x16_bf16 v[112:127], v[112:115], v[156:159], v[236:251]
	ds_read_b64_tr_b16 v[168:169], v255 offset:25600
	ds_read_b64_tr_b16 v[170:171], v255 offset:26112
	v_mfma_f32_32x32x16_bf16 v[96:111], v[196:199], v[152:155], v[96:111]
	v_add_f32_e32 v80, v90, v80
	v_add_f32_e32 v80, v91, v80
	v_add_f32_e32 v80, v92, v80
	v_add_f32_e32 v80, v93, v80
	v_cvt_pk_bf16_f32 v136, v88, v89
	v_cvt_pk_bf16_f32 v137, v90, v91
	ds_read_b64_tr_b16 v[172:173], v255 offset:29696
	ds_read_b64_tr_b16 v[174:175], v255 offset:30208
	v_add_f32_e32 v80, v94, v80
	v_add_f32_e32 v80, v95, v80
	v_add_f32_e32 v80, v64, v80
	v_add_f32_e32 v80, v65, v80
	v_cvt_pk_bf16_f32 v138, v92, v93
	v_cvt_pk_bf16_f32 v139, v94, v95
	v_mfma_f32_32x32x16_bf16 v[112:127], v[188:191], v[152:155], v[112:127]
	ds_read_b64_tr_b16 v[196:197], v255 offset:26624
	ds_read_b64_tr_b16 v[198:199], v255 offset:27136
	v_mfma_f32_32x32x16_bf16 v[96:111], v[184:187], v[148:151], v[96:111]
	v_add_f32_e32 v80, v66, v80
	v_add_f32_e32 v80, v67, v80
	v_add_f32_e32 v80, v68, v80
	v_add_f32_e32 v80, v69, v80
	v_cvt_pk_bf16_f32 v132, v64, v65
	v_cvt_pk_bf16_f32 v133, v66, v67
	ds_read_b64_tr_b16 v[184:185], v255 offset:30720
	ds_read_b64_tr_b16 v[186:187], v255 offset:31232
	v_add_f32_e32 v64, v70, v80
	v_add_f32_e32 v64, v71, v64
	v_add_f32_e32 v64, v72, v64
	v_add_f32_e32 v64, v73, v64
	v_cvt_pk_bf16_f32 v134, v68, v69
	v_cvt_pk_bf16_f32 v135, v70, v71
	v_mfma_f32_32x32x16_bf16 v[112:127], v[164:167], v[148:151], v[112:127]
	ds_read_b64_tr_b16 v[188:189], v255 offset:27648
	ds_read_b64_tr_b16 v[190:191], v255 offset:28160
	v_mfma_f32_32x32x16_bf16 v[96:111], v[180:183], v[144:147], v[96:111]
	v_add_f32_e32 v64, v74, v64
	v_add_f32_e32 v64, v75, v64
	v_add_f32_e32 v64, v76, v64
	v_add_f32_e32 v64, v77, v64
	v_cvt_pk_bf16_f32 v128, v72, v73
	v_cvt_pk_bf16_f32 v129, v74, v75
	ds_read_b64_tr_b16 v[192:193], v255 offset:31744
	ds_read_b64_tr_b16 v[194:195], v255 offset:32256
	v_add_f32_e32 v64, v78, v64
	v_mfma_f32_32x32x16_bf16 v[112:127], v[160:163], v[144:147], v[112:127]
	v_add_f32_e32 v160, v79, v64
	v_cvt_pk_bf16_f32 v130, v76, v77
	v_cvt_pk_bf16_f32 v131, v78, v79
	s_setprio 0
	s_add_i32 s0, s22, s26
	s_mov_b32 s1, m0
	s_mov_b32 m0, s0
	s_nop 0
	global_load_lds_dwordx4 v230, s[98:99]
	s_add_u32 s98, s98, 0x20000
	s_addc_u32 s99, s99, 0
	s_mov_b32 m0, s1
	s_lshl_b32 s0, s24, 1
	s_add_i32 s0, s0, s27
	s_mov_b32 s1, m0
	s_mov_b32 m0, s0
	s_nop 0
	global_load_lds_dwordx4 v228, s[86:87]
	s_add_u32 s86, s86, 0x20000
	s_addc_u32 s87, s87, 0
	s_mov_b32 m0, s1
	s_addk_i32 s0, 0x2000
	s_mov_b32 s1, m0
	s_mov_b32 m0, s0
	s_nop 0
	global_load_lds_dwordx4 v206, s[90:91]
	s_add_u32 s90, s90, 0x20000
	s_addc_u32 s91, s91, 0
	s_mov_b32 m0, s1
	v_max_f32_e32 v80, v96, v97
	v_max3_f32 v81, v98, v99, v113
	v_max3_f32 v80, v80, v112, v114
	v_max3_f32 v80, v80, v115, v100
	v_max3_f32 v81, v81, v102, v103
	v_max3_f32 v80, v80, v101, v116
	v_max3_f32 v81, v81, v118, v119
	v_max3_f32 v80, v80, v117, v104
	v_max3_f32 v81, v81, v106, v107
	v_max3_f32 v80, v80, v105, v120
	v_max3_f32 v81, v81, v122, v123
	v_max3_f32 v80, v80, v121, v108
	v_max3_f32 v81, v81, v110, v111
	v_max3_f32 v80, v80, v109, v124
	v_max3_f32 v81, v81, v126, v127
	v_max3_f32 v80, v80, v125, v81
	v_mov_b32_e32 v81, v80
	s_nop 1
	v_permlane32_swap_b32_e32 v80, v81
	v_max_f32_e32 v80, v80, v81
	v_cmp_lt_f32_e32 vcc, s56, v80
	s_cmp_lg_u64 vcc, 0
	v_add_f32_e32 v215, v215, v160
	s_cselect_b64 s[0:1], -1, 0
	s_cbranch_vccnz .LBB0_853

.LBB0_848:
	s_add_i32 s0, s24, 0x2000
	s_cmpk_lg_i32 s24, 0x4000
	s_cselect_b32 s0, s0, 0
	s_add_i32 s5, s5, 2
	s_cmpk_gt_u32 s5, 0x7c
	s_cbranch_scc1 .LBB0_856
	s_mov_b32 s36, s22
	s_mov_b32 s23, s24
	s_mov_b32 s22, s0
	s_branch .LBB0_842

.LBB0_856:
	s_add_u32 s90, s90, 0x20000
	s_addc_u32 s91, s91, 0
	v_lshl_add_u64 v[206:207], v[206:207], 0, s[90:91]
	s_mov_b64 s[90:91], 0x40000
	s_lshl_b32 s0, s73, 1
	s_and_b32 s5, s0, 0x780
	s_lshl_b64 s[0:1], s[12:13], 1
	s_add_u32 s0, s71, s0
	s_addc_u32 s1, s72, s1
	s_add_u32 s0, s0, s5
	s_mul_hi_i32 s14, s4, 0x1080000
	s_mul_i32 s4, s4, 0x1080000
	s_addc_u32 s1, s1, 0
	s_add_u32 s0, s0, s4
	s_addc_u32 s1, s1, s14
	v_lshl_add_u64 v[228:229], s[0:1], 0, v[208:209]
	s_mov_b64 s[0:1], 0x1040000
	v_lshl_add_u64 v[230:231], v[204:205], 0, s[0:1]
	s_movk_i32 s4, 0x7f
	s_movk_i32 s5, 0x4000
	s_movk_i32 s34, 0x2000
	s_mov_b32 s0, 0
	s_mov_b64 s[12:13], 0

.LBB0_899:
	s_mov_b32 s86, 0xffff0000
	s_movk_i32 s87, 0x1600
	v_mov_b64_e32 v[210:211], 0x100
	v_mov_b64_e32 v[212:213], 0xff
	v_mov_b32_e32 v218, 1
	v_mov_b32_e32 v219, 0x7f800000
	v_mov_b64_e32 v[220:221], 0x1ff
	v_mov_b32_e32 v236, 0x358637bd
	v_mov_b32_e32 v237, 0x260
	v_mov_b32_e32 v242, 0x1fcf
	v_mov_b32_e32 v243, 0xcf
	v_mov_b32_e32 v245, 0x80
	v_mov_b32_e32 v246, 0xc0
	v_readlane_b32 s0, v253, 21
	v_readlane_b32 s4, v252, 33
	v_readlane_b32 s1, v253, 22
	v_readlane_b32 s5, v252, 34
	s_or_b64 s[0:1], s[0:1], s[4:5]
	s_and_b64 vcc, exec, s[0:1]
	v_readlane_b32 s14, v253, 31
	v_readlane_b32 s15, v253, 1
	v_mov_b32_e32 v244, 0x2000
	s_cbranch_vccz .LBB0_907
